# gMLP item spatial GEMM: the eight weight-fragment global loads issued together before the barrier
# baseline (speedup 1.0000x reference)
.LBB0_309:
	s_or_b64 exec, exec, s[0:1]
	v_and_b32_e32 v6, 0x7f, v12
	v_or_b32_e32 v0, s4, v6
	v_readlane_b32 s2, v251, 25
	v_lshlrev_b32_e32 v0, 9, v0
	v_readlane_b32 s3, v251, 26
	s_and_b32 s0, s40, 3
	s_lshl_b32 s56, s0, 7
	v_lshl_add_u64 v[2:3], s[2:3], 0, v[0:1]
	v_ashrrev_i32_e32 v0, 2, v12
	v_and_b32_e32 v44, 0xffffffe0, v0
	v_lshl_add_u64 v[2:3], v[2:3], 0, s[56:57]
	v_ashrrev_i32_e32 v45, 31, v44
	v_lshl_add_u64 v[60:61], v[44:45], 1, v[2:3]
	s_waitcnt lgkmcnt(0)
	s_barrier
	global_load_dwordx4 v[14:17], v[60:61], off
	s_lshl_b32 s1, s0, 8
	v_readlane_b32 s2, v255, 3
	s_add_u32 s2, s2, s1
	v_readlane_b32 s3, v255, 4
	s_addc_u32 s3, s3, 0
	v_lshlrev_b64 v[2:3], 2, v[44:45]
	v_lshl_add_u64 v[8:9], s[2:3], 0, v[2:3]
	v_readlane_b32 s2, v255, 5
	s_add_u32 s2, s2, s1
	v_readlane_b32 s1, v255, 6
	s_addc_u32 s3, s1, 0
	v_lshl_add_u64 v[10:11], s[2:3], 0, v[2:3]
	global_load_dwordx4 v[18:21], v[10:11], off
	global_load_dwordx4 v[22:25], v[8:9], off
	global_load_dwordx4 v[26:29], v[8:9], off offset:16
	global_load_dwordx4 v[30:33], v[10:11], off offset:16
	global_load_dwordx4 v[2:5], v[60:61], off offset:16
	global_load_dwordx4 v[36:39], v[8:9], off offset:32
	global_load_dwordx4 v[40:43], v[10:11], off offset:32
	v_lshlrev_b32_e32 v0, 2, v6
	v_lshlrev_b32_e32 v13, 1, v6
	s_movk_i32 s5, 0x110
	ds_read2st64_b32 v[6:7], v0 offset0:68 offset1:70
	v_sub_u32_e32 v0, v0, v13
	v_mul_lo_u32 v44, v44, s5
	v_add_u32_e32 v0, v0, v44
	v_or_b32_e32 v13, v44, v13
	global_load_dwordx4 v[44:47], v[8:9], off offset:48
	global_load_dwordx4 v[48:51], v[8:9], off offset:80
	global_load_dwordx4 v[52:55], v[8:9], off offset:64
	global_load_dwordx4 v[56:59], v[60:61], off offset:48
	s_nop 0
	global_load_dwordx4 v[60:63], v[60:61], off offset:32
	s_nop 0
	global_load_dwordx4 v[64:67], v[10:11], off offset:48
	global_load_dwordx4 v[68:71], v[10:11], off offset:80
	global_load_dwordx4 v[72:75], v[10:11], off offset:64
	s_or_b32 s0, s0, s39
	s_ashr_i32 s1, s0, 31
	s_lshl_b64 s[2:3], s[0:1], 7
	v_and_b32_e32 v34, 31, v12
	v_bfe_u32 v35, v12, 5, 1
	v_readlane_b32 s8, v253, 51
	v_readlane_b32 s10, v253, 53
	v_readlane_b32 s11, v253, 54
	s_lshl_b64 s[0:1], s[0:1], 9
	s_mov_b64 s[6:7], s[10:11]
	s_add_u32 s0, s6, s0
	s_addc_u32 s1, s7, s1
	v_readlane_b32 s9, v253, 52
	v_readlane_b32 s12, v253, 55
	v_readlane_b32 s13, v253, 56
	v_readlane_b32 s14, v253, 57
	v_readlane_b32 s15, v253, 58
	v_readlane_b32 s16, v253, 59
	v_readlane_b32 s17, v253, 60
	v_readlane_b32 s18, v253, 61
	v_readlane_b32 s19, v253, 62
	v_readlane_b32 s20, v253, 63
	v_readlane_b32 s21, v254, 0
	v_readlane_b32 s22, v254, 1
	v_readlane_b32 s23, v254, 2
	s_mov_b64 s[6:7], -1
	s_waitcnt vmcnt(15)
	v_lshlrev_b32_e32 v76, 16, v14
	v_and_b32_e32 v14, 0xffff0000, v14
	v_lshlrev_b32_e32 v77, 16, v15
	v_and_b32_e32 v15, 0xffff0000, v15
	v_lshlrev_b32_e32 v78, 16, v16
	v_and_b32_e32 v16, 0xffff0000, v16
	s_waitcnt lgkmcnt(0)
	v_sub_f32_e32 v76, v76, v6
	v_sub_f32_e32 v14, v14, v6
	v_sub_f32_e32 v77, v77, v6
	v_sub_f32_e32 v15, v15, v6
	v_sub_f32_e32 v78, v78, v6
	v_sub_f32_e32 v16, v16, v6
	v_mul_f32_e32 v76, v7, v76
	v_mul_f32_e32 v14, v7, v14
	v_mul_f32_e32 v77, v7, v77
	v_mul_f32_e32 v15, v7, v15
	v_mul_f32_e32 v78, v7, v78
	v_mul_f32_e32 v16, v7, v16
	s_waitcnt vmcnt(13)
	v_fma_f32 v18, v22, v76, v18
	v_fma_f32 v14, v23, v14, v19
	v_fma_f32 v19, v77, v24, v20
	v_fmac_f32_e32 v21, v15, v25
	s_waitcnt vmcnt(11)
	v_fma_f32 v15, v78, v26, v30
	v_fma_f32 v16, v16, v27, v31
	v_bfe_u32 v22, v18, 16, 1
	v_bfe_u32 v23, v14, 16, 1
	v_lshlrev_b32_e32 v79, 16, v17
	v_bfe_u32 v24, v19, 16, 1
	v_bfe_u32 v25, v21, 16, 1
	v_bfe_u32 v26, v15, 16, 1
	v_bfe_u32 v27, v16, 16, 1
	v_add3_u32 v18, v18, v22, s37
	v_add3_u32 v14, v14, v23, s37
	v_sub_f32_e32 v79, v79, v6
	v_add3_u32 v19, v19, v24, s37
	v_add3_u32 v21, v21, v25, s37
	v_add3_u32 v15, v15, v26, s37
	v_add3_u32 v16, v16, v27, s37
	ds_write_b16_d16_hi v0, v18
	ds_write_b16_d16_hi v13, v14 offset:272
	ds_write_b16_d16_hi v0, v19 offset:544
	ds_write_b16_d16_hi v13, v21 offset:816
	ds_write_b16_d16_hi v0, v15 offset:1088
	ds_write_b16_d16_hi v13, v16 offset:1360
	v_and_b32_e32 v14, 0xffff0000, v17
	v_mul_f32_e32 v79, v7, v79
	v_sub_f32_e32 v14, v14, v6
	v_fma_f32 v20, v79, v28, v32
	v_mul_f32_e32 v14, v7, v14
	v_fmac_f32_e32 v33, v14, v29
	v_bfe_u32 v14, v20, 16, 1
	v_add3_u32 v14, v20, v14, s37
	ds_write_b16_d16_hi v0, v14 offset:1632
	v_bfe_u32 v14, v33, 16, 1
	v_add3_u32 v14, v33, v14, s37
	ds_write_b16_d16_hi v13, v14 offset:1904
	s_waitcnt vmcnt(10)
	v_lshlrev_b32_e32 v14, 16, v2
	v_sub_f32_e32 v14, v14, v6
	v_mul_f32_e32 v14, v7, v14
	v_and_b32_e32 v2, 0xffff0000, v2
	s_waitcnt vmcnt(8)
	v_fma_f32 v14, v36, v14, v40
	v_sub_f32_e32 v2, v2, v6
	v_mul_f32_e32 v2, v7, v2
	v_bfe_u32 v15, v14, 16, 1
	v_fma_f32 v2, v37, v2, v41
	v_add3_u32 v14, v14, v15, s37
	ds_write_b16_d16_hi v0, v14 offset:2176
	v_bfe_u32 v14, v2, 16, 1
	v_add3_u32 v2, v2, v14, s37
	ds_write_b16_d16_hi v13, v2 offset:2448
	v_lshlrev_b32_e32 v2, 16, v3
	v_sub_f32_e32 v2, v2, v6
	v_and_b32_e32 v3, 0xffff0000, v3
	v_mul_f32_e32 v2, v7, v2
	v_sub_f32_e32 v3, v3, v6
	v_fma_f32 v2, v2, v38, v42
	v_mul_f32_e32 v3, v7, v3
	v_fmac_f32_e32 v43, v3, v39
	v_bfe_u32 v3, v2, 16, 1
	v_add3_u32 v2, v2, v3, s37
	ds_write_b16_d16_hi v0, v2 offset:2720
	v_bfe_u32 v2, v43, 16, 1
	v_add3_u32 v2, v43, v2, s37
	ds_write_b16_d16_hi v13, v2 offset:2992
	global_load_dwordx4 v[14:17], v[8:9], off offset:112
	global_load_dwordx4 v[18:21], v[8:9], off offset:96
	global_load_dwordx4 v[22:25], v[10:11], off offset:112
	s_nop 0
	global_load_dwordx4 v[8:11], v[10:11], off offset:96
	v_lshlrev_b32_e32 v2, 16, v4
	v_sub_f32_e32 v2, v2, v6
	v_mul_f32_e32 v2, v7, v2
	v_and_b32_e32 v3, 0xffff0000, v4
	s_waitcnt vmcnt(6)
	v_fma_f32 v2, v2, v44, v64
	v_sub_f32_e32 v3, v3, v6
	v_mul_f32_e32 v3, v7, v3
	v_bfe_u32 v4, v2, 16, 1
	v_fma_f32 v3, v3, v45, v65
	v_add3_u32 v2, v2, v4, s37
	ds_write_b16_d16_hi v0, v2 offset:3264
	v_bfe_u32 v2, v3, 16, 1
	v_add3_u32 v2, v3, v2, s37
	ds_write_b16_d16_hi v13, v2 offset:3536
	v_lshlrev_b32_e32 v2, 16, v5
	v_sub_f32_e32 v2, v2, v6
	v_and_b32_e32 v3, 0xffff0000, v5
	v_mul_f32_e32 v2, v7, v2
	v_sub_f32_e32 v3, v3, v6
	v_fma_f32 v2, v2, v46, v66
	v_mul_f32_e32 v3, v7, v3
	v_fmac_f32_e32 v67, v3, v47
	v_bfe_u32 v3, v2, 16, 1
	v_add3_u32 v2, v2, v3, s37
	ds_write_b16_d16_hi v0, v2 offset:3808
	v_bfe_u32 v2, v67, 16, 1
	v_add3_u32 v2, v67, v2, s37
	ds_write_b16_d16_hi v13, v2 offset:4080
	v_lshlrev_b32_e32 v2, 16, v60
	v_sub_f32_e32 v2, v2, v6
	v_mul_f32_e32 v2, v7, v2
	v_and_b32_e32 v3, 0xffff0000, v60
	s_waitcnt vmcnt(4)
	v_fma_f32 v2, v52, v2, v72
	v_sub_f32_e32 v3, v3, v6
	v_mul_f32_e32 v3, v7, v3
	v_bfe_u32 v4, v2, 16, 1
	v_fma_f32 v3, v53, v3, v73
	v_add3_u32 v2, v2, v4, s37
	ds_write_b16_d16_hi v0, v2 offset:4352
	v_bfe_u32 v2, v3, 16, 1
	v_add3_u32 v2, v3, v2, s37
	ds_write_b16_d16_hi v13, v2 offset:4624
	v_lshlrev_b32_e32 v2, 16, v61
	v_sub_f32_e32 v2, v2, v6
	v_and_b32_e32 v3, 0xffff0000, v61
	v_mul_f32_e32 v2, v7, v2
	v_sub_f32_e32 v3, v3, v6
	v_fma_f32 v2, v2, v54, v74
	v_mul_f32_e32 v3, v7, v3
	v_fmac_f32_e32 v75, v3, v55
	v_bfe_u32 v3, v2, 16, 1
	v_add3_u32 v2, v2, v3, s37
	ds_write_b16_d16_hi v0, v2 offset:4896
	v_bfe_u32 v2, v75, 16, 1
	v_add3_u32 v2, v75, v2, s37
	ds_write_b16_d16_hi v13, v2 offset:5168
	v_lshlrev_b32_e32 v2, 16, v62
	v_sub_f32_e32 v2, v2, v6
	v_mul_f32_e32 v2, v7, v2
	v_and_b32_e32 v3, 0xffff0000, v62
	v_fma_f32 v2, v2, v48, v68
	v_sub_f32_e32 v3, v3, v6
	v_mul_f32_e32 v3, v7, v3
	v_bfe_u32 v4, v2, 16, 1
	v_fma_f32 v3, v3, v49, v69
	v_add3_u32 v2, v2, v4, s37
	ds_write_b16_d16_hi v0, v2 offset:5440
	v_bfe_u32 v2, v3, 16, 1
	v_add3_u32 v2, v3, v2, s37
	ds_write_b16_d16_hi v13, v2 offset:5712
	v_lshlrev_b32_e32 v2, 16, v63
	v_sub_f32_e32 v2, v2, v6
	v_and_b32_e32 v3, 0xffff0000, v63
	v_mul_f32_e32 v2, v7, v2
	v_sub_f32_e32 v3, v3, v6
	v_fma_f32 v2, v2, v50, v70
	v_mul_f32_e32 v3, v7, v3
	v_fmac_f32_e32 v71, v3, v51
	v_bfe_u32 v3, v2, 16, 1
	v_add3_u32 v2, v2, v3, s37
	ds_write_b16_d16_hi v0, v2 offset:5984
	v_bfe_u32 v2, v71, 16, 1
	v_add3_u32 v2, v71, v2, s37
	ds_write_b16_d16_hi v13, v2 offset:6256
	v_lshlrev_b32_e32 v2, 16, v56
	v_sub_f32_e32 v2, v2, v6
	v_mul_f32_e32 v2, v7, v2
	v_and_b32_e32 v3, 0xffff0000, v56
	s_waitcnt vmcnt(0)
	v_fma_f32 v2, v18, v2, v8
	v_sub_f32_e32 v3, v3, v6
	v_mul_f32_e32 v3, v7, v3
	v_bfe_u32 v4, v2, 16, 1
	v_fma_f32 v3, v19, v3, v9
	v_add3_u32 v2, v2, v4, s37
	ds_write_b16_d16_hi v0, v2 offset:6528
	v_bfe_u32 v2, v3, 16, 1
	v_add3_u32 v2, v3, v2, s37
	ds_write_b16_d16_hi v13, v2 offset:6800
	v_lshlrev_b32_e32 v2, 16, v57
	v_sub_f32_e32 v2, v2, v6
	v_and_b32_e32 v3, 0xffff0000, v57
	v_mul_f32_e32 v2, v7, v2
	v_sub_f32_e32 v3, v3, v6
	v_fma_f32 v2, v2, v20, v10
	v_mul_f32_e32 v3, v7, v3
	v_fmac_f32_e32 v11, v3, v21
	v_bfe_u32 v3, v2, 16, 1
	v_add3_u32 v2, v2, v3, s37
	ds_write_b16_d16_hi v0, v2 offset:7072
	v_bfe_u32 v2, v11, 16, 1
	v_add3_u32 v2, v11, v2, s37
	ds_write_b16_d16_hi v13, v2 offset:7344
	v_lshlrev_b32_e32 v2, 16, v58
	v_sub_f32_e32 v2, v2, v6
	v_mul_f32_e32 v2, v7, v2
	v_and_b32_e32 v3, 0xffff0000, v58
	v_fma_f32 v2, v2, v14, v22
	v_sub_f32_e32 v3, v3, v6
	v_mul_f32_e32 v3, v7, v3
	v_bfe_u32 v4, v2, 16, 1
	v_fma_f32 v3, v3, v15, v23
	v_add3_u32 v2, v2, v4, s37
	ds_write_b16_d16_hi v0, v2 offset:7616
	v_bfe_u32 v2, v3, 16, 1
	v_add3_u32 v2, v3, v2, s37
	ds_write_b16_d16_hi v13, v2 offset:7888
	v_lshlrev_b32_e32 v2, 16, v59
	v_sub_f32_e32 v2, v2, v6
	v_and_b32_e32 v3, 0xffff0000, v59
	v_mul_f32_e32 v2, v7, v2
	v_sub_f32_e32 v3, v3, v6
	v_fma_f32 v2, v2, v16, v24
	v_mul_f32_e32 v3, v7, v3
	v_fmac_f32_e32 v25, v3, v17
	v_bfe_u32 v3, v2, 16, 1
	v_add3_u32 v2, v2, v3, s37
	ds_write_b16_d16_hi v0, v2 offset:8160
	v_bfe_u32 v0, v25, 16, 1
	v_add3_u32 v0, v25, v0, s37
	ds_write_b16_d16_hi v13, v0 offset:8432
	v_ashrrev_i32_e32 v0, 1, v12
	v_and_b32_e32 v56, 0xffffffe0, v0
	v_ashrrev_i32_e32 v57, 31, v56
	v_lshl_add_u64 v[2:3], s[2:3], 0, v[56:57]
	v_or_b32_e32 v2, v2, v34
	v_readlane_b32 s2, v250, 52
	v_lshlrev_b64 v[2:3], 8, v[2:3]
	v_readlane_b32 s3, v250, 53
	v_lshlrev_b32_e32 v0, 4, v35
	s_waitcnt lgkmcnt(0)
	v_lshl_add_u64 v[2:3], s[2:3], 0, v[2:3]
	v_lshl_add_u64 v[62:63], v[2:3], 0, v[0:1]
	global_load_dwordx4 v[120:123], v[62:63], off
	global_load_dwordx4 v[124:127], v[62:63], off offset:32
	global_load_dwordx4 v[128:131], v[62:63], off offset:64
	global_load_dwordx4 v[132:135], v[62:63], off offset:96
	global_load_dwordx4 v[136:139], v[62:63], off offset:128
	global_load_dwordx4 v[140:143], v[62:63], off offset:160
	global_load_dwordx4 v[144:147], v[62:63], off offset:192
	global_load_dwordx4 v[148:151], v[62:63], off offset:224
	s_barrier
	v_mad_u32_u24 v66, v34, s5, v0
	ds_read_b128 v[2:5], v66
	ds_read_b128 v[40:43], v66 offset:32
	s_waitcnt vmcnt(0) lgkmcnt(1)
	v_mfma_f32_32x32x16_bf16 v[2:17], v[120:123], v[2:5], 0
	ds_read_b128 v[22:25], v66 offset:8704
	ds_read_b128 v[44:47], v66 offset:8736
	v_readlane_b32 s2, v251, 27
	s_add_u32 s2, s2, s56
	v_readlane_b32 s3, v251, 28
	s_addc_u32 s3, s3, 0
	v_lshlrev_b32_e32 v0, 1, v34
	s_waitcnt lgkmcnt(2)
	v_mfma_f32_32x32x16_bf16 v[2:17], v[124:127], v[40:43], v[2:17]
	s_waitcnt lgkmcnt(1)
	v_mfma_f32_32x32x16_bf16 v[18:33], v[120:123], v[22:25], 0
	s_waitcnt lgkmcnt(0)
	v_mfma_f32_32x32x16_bf16 v[18:33], v[124:127], v[44:47], v[18:33]
	ds_read_b128 v[44:47], v66 offset:64
	ds_read_b128 v[48:51], v66 offset:96
	s_waitcnt lgkmcnt(1)
	v_mfma_f32_32x32x16_bf16 v[2:17], v[128:131], v[44:47], v[2:17]
	ds_read_b128 v[44:47], v66 offset:8768
	ds_read_b128 v[52:55], v66 offset:8800
	s_waitcnt lgkmcnt(1)
	v_mfma_f32_32x32x16_bf16 v[18:33], v[128:131], v[44:47], v[18:33]
	v_mfma_f32_32x32x16_bf16 v[2:17], v[132:135], v[48:51], v[2:17]
	s_waitcnt lgkmcnt(0)
	v_mfma_f32_32x32x16_bf16 v[18:33], v[132:135], v[52:55], v[18:33]
	ds_read_b128 v[44:47], v66 offset:128
	ds_read_b128 v[48:51], v66 offset:160
	s_waitcnt lgkmcnt(1)
	v_mfma_f32_32x32x16_bf16 v[2:17], v[136:139], v[44:47], v[2:17]
	ds_read_b128 v[44:47], v66 offset:8832
	ds_read_b128 v[52:55], v66 offset:8864
	s_waitcnt lgkmcnt(1)
	v_mfma_f32_32x32x16_bf16 v[18:33], v[136:139], v[44:47], v[18:33]
	ds_read_b128 v[42:45], v66 offset:224
	v_mfma_f32_32x32x16_bf16 v[2:17], v[140:143], v[48:51], v[2:17]
	ds_read_b128 v[46:49], v66 offset:192
	s_waitcnt lgkmcnt(2)
	v_mfma_f32_32x32x16_bf16 v[18:33], v[140:143], v[52:55], v[18:33]
	v_lshl_or_b32 v36, v35, 2, v56
	v_add_u32_e32 v50, s4, v36
	v_ashrrev_i32_e32 v51, 31, v50
	v_lshl_add_u64 v[52:53], s[2:3], 0, v[0:1]
	v_ashrrev_i32_e32 v37, 31, v36
	v_lshl_add_u64 v[54:55], v[36:37], 2, s[0:1]
	s_waitcnt lgkmcnt(0)
	v_mfma_f32_32x32x16_bf16 v[2:17], v[144:147], v[46:49], v[2:17]
	v_lshlrev_b64 v[46:47], 9, v[50:51]
	v_lshl_add_u64 v[56:57], v[52:53], 0, v[46:47]
	global_load_ushort v67, v[56:57], off
	global_load_dwordx4 v[34:37], v[54:55], off
	ds_read_b128 v[62:65], v66 offset:8896
	ds_read_b128 v[46:49], v66 offset:8928
	s_add_u32 s0, s94, s56
	s_addc_u32 s1, s95, 0
	s_waitcnt lgkmcnt(1)
	v_mfma_f32_32x32x16_bf16 v[18:33], v[144:147], v[62:65], v[18:33]
	global_load_ushort v64, v[56:57], off offset:64
	s_mov_b32 s98, 0x1000
	s_mov_b32 s99, 0
	v_lshl_add_u64 v[100:101], v[56:57], 0, s[98:99]
	v_lshl_add_u64 v[102:103], v[100:101], 0, s[98:99]
	v_lshl_add_u64 v[104:105], v[102:103], 0, s[98:99]
	global_load_ushort v68, v[56:57], off offset:512
	global_load_ushort v69, v[56:57], off offset:576
	global_load_ushort v70, v[56:57], off offset:1024
	global_load_ushort v71, v[56:57], off offset:1088
	global_load_ushort v72, v[56:57], off offset:1536
	global_load_ushort v73, v[56:57], off offset:1600
	global_load_ushort v74, v[100:101], off
	global_load_ushort v75, v[100:101], off offset:64
	global_load_ushort v76, v[100:101], off offset:512
	global_load_ushort v77, v[100:101], off offset:576
	global_load_ushort v78, v[100:101], off offset:1024
	global_load_ushort v79, v[100:101], off offset:1088
	global_load_ushort v80, v[100:101], off offset:1536
	global_load_ushort v81, v[100:101], off offset:1600
	global_load_ushort v82, v[102:103], off
	global_load_ushort v83, v[102:103], off offset:64
	global_load_ushort v84, v[102:103], off offset:512
	global_load_ushort v85, v[102:103], off offset:576
	global_load_ushort v86, v[102:103], off offset:1024
	global_load_ushort v87, v[102:103], off offset:1088
	global_load_ushort v88, v[102:103], off offset:1536
	global_load_ushort v89, v[102:103], off offset:1600
	global_load_ushort v90, v[104:105], off
	global_load_ushort v91, v[104:105], off offset:64
	global_load_ushort v92, v[104:105], off offset:512
	global_load_ushort v93, v[104:105], off offset:576
	global_load_ushort v94, v[104:105], off offset:1024
	global_load_ushort v95, v[104:105], off offset:1088
	global_load_ushort v96, v[104:105], off offset:1536
	global_load_ushort v97, v[104:105], off offset:1600
	global_load_dwordx4 v[106:109], v[54:55], off offset:32
	global_load_dwordx4 v[110:113], v[54:55], off offset:64
	global_load_dwordx4 v[114:117], v[54:55], off offset:96
	v_add_u32_e32 v60, 1, v50
	v_ashrrev_i32_e32 v61, 31, v60
	v_lshlrev_b64 v[62:63], 9, v[60:61]
	v_lshl_add_u64 v[62:63], v[52:53], 0, v[62:63]
	s_waitcnt vmcnt(3)
	v_mfma_f32_32x32x16_bf16 v[2:17], v[148:151], v[42:45], v[2:17]
	v_lshl_add_u64 v[42:43], s[0:1], 0, v[0:1]
	v_lshlrev_b64 v[44:45], 11, v[50:51]
	v_lshl_add_u64 v[44:45], v[42:43], 0, v[44:45]
	v_add_co_u32_e32 v44, vcc, s35, v44
	s_waitcnt vmcnt(2)
	v_lshlrev_b32_e32 v0, 16, v67
	s_waitcnt lgkmcnt(0)
	v_mfma_f32_32x32x16_bf16 v[18:33], v[148:151], v[46:49], v[18:33]
	s_waitcnt vmcnt(1)
	s_nop 2
	v_add_f32_e32 v2, v2, v34
	v_mul_f32_e32 v0, v2, v0
	v_bfe_u32 v2, v0, 16, 1
	v_add3_u32 v0, v0, v2, s37
	v_addc_co_u32_e32 v45, vcc, 0, v45, vcc
	global_store_short_d16_hi v[44:45], v0, off offset:1792
	s_waitcnt vmcnt(0)
	v_mov_b32_e32 v0, v68
	v_lshlrev_b32_e32 v2, 16, v64
	v_add_f32_e32 v18, v18, v34
	v_mul_f32_e32 v2, v18, v2
	v_bfe_u32 v18, v2, 16, 1
	v_add3_u32 v2, v2, v18, s37
	global_store_short_d16_hi v[44:45], v2, off offset:1856
	v_mov_b32_e32 v18, v69
	v_add_f32_e32 v2, v3, v35
	v_add_u32_e32 v38, 2, v50
	v_ashrrev_i32_e32 v39, 31, v38
	v_lshlrev_b64 v[40:41], 9, v[38:39]
	v_lshl_add_u64 v[40:41], v[52:53], 0, v[40:41]
	v_add_f32_e32 v19, v19, v35
	v_add_f32_e32 v4, v4, v36
	v_mov_b64_e32 v[56:57], v[106:107]
	v_mov_b64_e32 v[58:59], v[108:109]
	v_add_f32_e32 v5, v5, v37
	v_lshlrev_b32_e32 v0, 16, v0
	v_mul_f32_e32 v0, v2, v0
	v_bfe_u32 v2, v0, 16, 1
	v_add3_u32 v0, v0, v2, s37
	v_lshlrev_b64 v[2:3], 11, v[60:61]
	v_lshl_add_u64 v[2:3], v[42:43], 0, v[2:3]
	v_add_co_u32_e32 v2, vcc, s35, v2
	v_lshlrev_b32_e32 v18, 16, v18
	v_addc_co_u32_e32 v3, vcc, 0, v3, vcc
	global_store_short_d16_hi v[2:3], v0, off offset:1792
	v_mov_b32_e32 v0, v70
	v_mul_f32_e32 v18, v19, v18
	v_bfe_u32 v19, v18, 16, 1
	v_add3_u32 v18, v18, v19, s37
	global_store_short_d16_hi v[2:3], v18, off offset:1856
	v_mov_b32_e32 v40, v71
	v_lshlrev_b64 v[18:19], 11, v[38:39]
	v_lshl_add_u64 v[18:19], v[42:43], 0, v[18:19]
	v_add_co_u32_e32 v18, vcc, s35, v18
	v_add_u32_e32 v2, 3, v50
	s_nop 0
	v_addc_co_u32_e32 v19, vcc, 0, v19, vcc
	v_ashrrev_i32_e32 v3, 31, v2
	v_lshlrev_b64 v[34:35], 9, v[2:3]
	v_lshl_add_u64 v[34:35], v[52:53], 0, v[34:35]
	v_lshlrev_b64 v[2:3], 11, v[2:3]
	v_lshl_add_u64 v[2:3], v[42:43], 0, v[2:3]
	v_add_co_u32_e32 v2, vcc, s35, v2
	v_add_f32_e32 v6, v6, v56
	v_addc_co_u32_e32 v3, vcc, 0, v3, vcc
	v_add_f32_e32 v7, v7, v57
	v_add_f32_e32 v8, v8, v58
	v_add_f32_e32 v9, v9, v59
	v_lshlrev_b32_e32 v0, 16, v0
	v_mul_f32_e32 v0, v4, v0
	v_bfe_u32 v4, v0, 16, 1
	v_add3_u32 v0, v0, v4, s37
	global_store_short_d16_hi v[18:19], v0, off offset:1792
	v_lshlrev_b32_e32 v0, 16, v40
	v_add_f32_e32 v4, v20, v36
	v_mul_f32_e32 v0, v4, v0
	v_bfe_u32 v4, v0, 16, 1
	v_add3_u32 v0, v0, v4, s37
	global_store_short_d16_hi v[18:19], v0, off offset:1856
	v_mov_b32_e32 v0, v72
	s_nop 0
	v_mov_b32_e32 v4, v73
	v_add_u32_e32 v18, 8, v50
	v_add_f32_e32 v20, v21, v37
	v_ashrrev_i32_e32 v19, 31, v18
	v_lshlrev_b64 v[34:35], 9, v[18:19]
	v_lshl_add_u64 v[34:35], v[52:53], 0, v[34:35]
	v_add_f32_e32 v21, v22, v56
	v_add_f32_e32 v22, v25, v59
	v_lshlrev_b32_e32 v0, 16, v0
	v_lshlrev_b32_e32 v4, 16, v4
	v_mul_f32_e32 v0, v5, v0
	v_mul_f32_e32 v4, v20, v4
	v_bfe_u32 v5, v0, 16, 1
	v_bfe_u32 v20, v4, 16, 1
	v_add3_u32 v0, v0, v5, s37
	v_add3_u32 v4, v4, v20, s37
	global_store_short_d16_hi v[2:3], v0, off offset:1792
	global_store_short_d16_hi v[2:3], v4, off offset:1856
	v_mov_b32_e32 v0, v74
	s_nop 0
	v_mov_b32_e32 v20, v75
	v_lshlrev_b64 v[4:5], 11, v[18:19]
	v_add_u32_e32 v2, 9, v50
	v_lshl_add_u64 v[4:5], v[42:43], 0, v[4:5]
	v_ashrrev_i32_e32 v3, 31, v2
	v_add_co_u32_e32 v4, vcc, s35, v4
	v_lshlrev_b64 v[18:19], 9, v[2:3]
	s_nop 0
	v_addc_co_u32_e32 v5, vcc, 0, v5, vcc
	v_lshl_add_u64 v[18:19], v[52:53], 0, v[18:19]
	v_lshlrev_b64 v[2:3], 11, v[2:3]
	v_lshl_add_u64 v[2:3], v[42:43], 0, v[2:3]
	v_add_co_u32_e32 v2, vcc, s35, v2
	v_lshlrev_b32_e32 v0, 16, v0
	v_lshlrev_b32_e32 v20, 16, v20
	v_mul_f32_e32 v0, v6, v0
	v_mul_f32_e32 v6, v21, v20
	v_bfe_u32 v20, v0, 16, 1
	v_bfe_u32 v21, v6, 16, 1
	v_add3_u32 v0, v0, v20, s37
	v_add3_u32 v6, v6, v21, s37
	global_store_short_d16_hi v[4:5], v0, off offset:1792
	global_store_short_d16_hi v[4:5], v6, off offset:1856
	v_mov_b32_e32 v0, v76
	s_nop 0
	v_mov_b32_e32 v6, v77
	v_add_u32_e32 v4, 10, v50
	v_add_f32_e32 v20, v23, v57
	v_ashrrev_i32_e32 v5, 31, v4
	v_lshlrev_b64 v[18:19], 9, v[4:5]
	v_addc_co_u32_e32 v3, vcc, 0, v3, vcc
	v_lshl_add_u64 v[18:19], v[52:53], 0, v[18:19]
	v_lshlrev_b64 v[4:5], 11, v[4:5]
	v_lshl_add_u64 v[4:5], v[42:43], 0, v[4:5]
	v_add_co_u32_e32 v4, vcc, s35, v4
	v_lshlrev_b32_e32 v0, 16, v0
	v_lshlrev_b32_e32 v6, 16, v6
	v_mul_f32_e32 v0, v7, v0
	v_mul_f32_e32 v6, v20, v6
	v_bfe_u32 v7, v0, 16, 1
	v_bfe_u32 v20, v6, 16, 1
	v_add3_u32 v0, v0, v7, s37
	v_add3_u32 v6, v6, v20, s37
	global_store_short_d16_hi v[2:3], v0, off offset:1792
	global_store_short_d16_hi v[2:3], v6, off offset:1856
	v_mov_b32_e32 v0, v78
	s_nop 0
	v_mov_b32_e32 v18, v79
	v_add_u32_e32 v2, 11, v50
	v_add_f32_e32 v19, v24, v58
	v_ashrrev_i32_e32 v3, 31, v2
	v_lshlrev_b64 v[6:7], 9, v[2:3]
	v_addc_co_u32_e32 v5, vcc, 0, v5, vcc
	v_lshl_add_u64 v[6:7], v[52:53], 0, v[6:7]
	v_lshlrev_b64 v[2:3], 11, v[2:3]
	v_lshl_add_u64 v[2:3], v[42:43], 0, v[2:3]
	v_add_co_u32_e32 v20, vcc, s35, v2
	v_lshlrev_b32_e32 v0, 16, v0
	v_lshlrev_b32_e32 v18, 16, v18
	v_mul_f32_e32 v0, v8, v0
	v_mul_f32_e32 v8, v19, v18
	v_bfe_u32 v18, v0, 16, 1
	v_bfe_u32 v19, v8, 16, 1
	v_add3_u32 v0, v0, v18, s37
	v_add3_u32 v8, v8, v19, s37
	global_store_short_d16_hi v[4:5], v0, off offset:1792
	global_store_short_d16_hi v[4:5], v8, off offset:1856
	v_mov_b32_e32 v0, v80
	s_nop 0
	v_mov_b32_e32 v8, v81
	v_add_u32_e32 v6, 16, v50
	v_ashrrev_i32_e32 v7, 31, v6
	v_lshlrev_b64 v[4:5], 9, v[6:7]
	v_addc_co_u32_e32 v21, vcc, 0, v3, vcc
	v_lshl_add_u64 v[18:19], v[52:53], 0, v[4:5]
	v_mov_b64_e32 v[2:3], v[110:111]
	v_mov_b64_e32 v[4:5], v[112:113]
	v_lshlrev_b64 v[6:7], 11, v[6:7]
	v_lshl_add_u64 v[6:7], v[42:43], 0, v[6:7]
	v_lshlrev_b32_e32 v0, 16, v0
	v_lshlrev_b32_e32 v8, 16, v8
	v_mul_f32_e32 v0, v9, v0
	v_mul_f32_e32 v8, v22, v8
	v_bfe_u32 v9, v0, 16, 1
	v_bfe_u32 v22, v8, 16, 1
	v_add3_u32 v0, v0, v9, s37
	v_add3_u32 v8, v8, v22, s37
	global_store_short_d16_hi v[20:21], v0, off offset:1792
	global_store_short_d16_hi v[20:21], v8, off offset:1856
	v_mov_b32_e32 v0, v82
	s_nop 0
	v_mov_b32_e32 v24, v83
	v_add_f32_e32 v10, v10, v2
	v_add_u32_e32 v18, 17, v50
	v_add_f32_e32 v2, v26, v2
	v_ashrrev_i32_e32 v19, 31, v18
	v_add_co_u32_e32 v22, vcc, s35, v6
	v_lshlrev_b64 v[8:9], 9, v[18:19]
	s_nop 0
	v_addc_co_u32_e32 v23, vcc, 0, v7, vcc
	v_lshl_add_u64 v[20:21], v[52:53], 0, v[8:9]
	v_mov_b64_e32 v[6:7], v[114:115]
	v_mov_b64_e32 v[8:9], v[116:117]
	v_lshlrev_b64 v[18:19], 11, v[18:19]
	v_lshl_add_u64 v[18:19], v[42:43], 0, v[18:19]
	v_add_co_u32_e32 v18, vcc, s35, v18
	v_add_f32_e32 v12, v12, v4
	s_nop 0
	v_addc_co_u32_e32 v19, vcc, 0, v19, vcc
	v_add_f32_e32 v4, v28, v4
	v_lshlrev_b32_e32 v0, 16, v0
	v_lshlrev_b32_e32 v24, 16, v24
	v_mul_f32_e32 v0, v10, v0
	v_mul_f32_e32 v2, v2, v24
	v_bfe_u32 v10, v0, 16, 1
	v_bfe_u32 v24, v2, 16, 1
	v_add3_u32 v0, v0, v10, s37
	v_add3_u32 v2, v2, v24, s37
	global_store_short_d16_hi v[22:23], v0, off offset:1792
	global_store_short_d16_hi v[22:23], v2, off offset:1856
	v_mov_b32_e32 v0, v84
	s_nop 0
	v_mov_b32_e32 v2, v85
	v_add_f32_e32 v10, v11, v3
	v_add_u32_e32 v20, 18, v50
	v_add_f32_e32 v3, v27, v3
	v_ashrrev_i32_e32 v21, 31, v20
	v_lshlrev_b64 v[22:23], 9, v[20:21]
	v_lshl_add_u64 v[22:23], v[52:53], 0, v[22:23]
	v_lshlrev_b32_e32 v0, 16, v0
	v_lshlrev_b32_e32 v2, 16, v2
	v_mul_f32_e32 v0, v10, v0
	v_mul_f32_e32 v2, v3, v2
	v_bfe_u32 v3, v0, 16, 1
	v_bfe_u32 v10, v2, 16, 1
	v_add3_u32 v0, v0, v3, s37
	v_add3_u32 v2, v2, v10, s37
	global_store_short_d16_hi v[18:19], v0, off offset:1792
	global_store_short_d16_hi v[18:19], v2, off offset:1856
	v_mov_b32_e32 v0, v86
	s_nop 0
	v_mov_b32_e32 v22, v87
	v_lshlrev_b64 v[10:11], 11, v[20:21]
	v_add_u32_e32 v2, 19, v50
	v_lshl_add_u64 v[10:11], v[42:43], 0, v[10:11]
	v_ashrrev_i32_e32 v3, 31, v2
	v_add_co_u32_e32 v10, vcc, s35, v10
	v_lshlrev_b64 v[18:19], 9, v[2:3]
	s_nop 0
	v_addc_co_u32_e32 v11, vcc, 0, v11, vcc
	v_lshl_add_u64 v[18:19], v[52:53], 0, v[18:19]
	v_lshlrev_b64 v[2:3], 11, v[2:3]
	v_lshl_add_u64 v[2:3], v[42:43], 0, v[2:3]
	v_add_co_u32_e32 v2, vcc, s35, v2
	v_lshlrev_b32_e32 v0, 16, v0
	v_lshlrev_b32_e32 v20, 16, v22
	v_mul_f32_e32 v0, v12, v0
	v_mul_f32_e32 v4, v4, v20
	v_bfe_u32 v12, v0, 16, 1
	v_bfe_u32 v20, v4, 16, 1
	v_add3_u32 v0, v0, v12, s37
	v_add3_u32 v4, v4, v20, s37
	global_store_short_d16_hi v[10:11], v0, off offset:1792
	global_store_short_d16_hi v[10:11], v4, off offset:1856
	v_mov_b32_e32 v0, v88
	s_nop 0
	v_mov_b32_e32 v4, v89
	v_add_f32_e32 v12, v13, v5
	v_add_u32_e32 v10, 24, v50
	v_add_f32_e32 v5, v29, v5
	v_ashrrev_i32_e32 v11, 31, v10
	v_lshlrev_b64 v[18:19], 9, v[10:11]
	v_addc_co_u32_e32 v3, vcc, 0, v3, vcc
	v_lshl_add_u64 v[18:19], v[52:53], 0, v[18:19]
	v_add_f32_e32 v13, v14, v6
	v_add_f32_e32 v6, v30, v6
	v_lshlrev_b32_e32 v0, 16, v0
	v_lshlrev_b32_e32 v4, 16, v4
	v_mul_f32_e32 v0, v12, v0
	v_mul_f32_e32 v4, v5, v4
	v_bfe_u32 v5, v0, 16, 1
	v_bfe_u32 v12, v4, 16, 1
	v_add3_u32 v0, v0, v5, s37
	v_add3_u32 v4, v4, v12, s37
	global_store_short_d16_hi v[2:3], v0, off offset:1792
	global_store_short_d16_hi v[2:3], v4, off offset:1856
	v_mov_b32_e32 v0, v90
	s_nop 0
	v_mov_b32_e32 v12, v91
	v_lshlrev_b64 v[4:5], 11, v[10:11]
	v_add_u32_e32 v2, 25, v50
	v_lshl_add_u64 v[4:5], v[42:43], 0, v[4:5]
	v_ashrrev_i32_e32 v3, 31, v2
	v_add_co_u32_e32 v4, vcc, s35, v4
	v_lshlrev_b64 v[10:11], 9, v[2:3]
	s_nop 0
	v_addc_co_u32_e32 v5, vcc, 0, v5, vcc
	v_lshl_add_u64 v[10:11], v[52:53], 0, v[10:11]
	v_lshlrev_b64 v[2:3], 11, v[2:3]
	v_lshl_add_u64 v[2:3], v[42:43], 0, v[2:3]
	v_add_co_u32_e32 v2, vcc, s35, v2
	v_lshlrev_b32_e32 v0, 16, v0
	v_lshlrev_b32_e32 v12, 16, v12
	v_mul_f32_e32 v0, v13, v0
	v_mul_f32_e32 v6, v6, v12
	v_bfe_u32 v12, v0, 16, 1
	v_bfe_u32 v13, v6, 16, 1
	v_add3_u32 v0, v0, v12, s37
	v_add3_u32 v6, v6, v13, s37
	global_store_short_d16_hi v[4:5], v0, off offset:1792
	global_store_short_d16_hi v[4:5], v6, off offset:1856
	v_mov_b32_e32 v0, v92
	s_nop 0
	v_mov_b32_e32 v6, v93
	v_add_f32_e32 v12, v15, v7
	v_add_u32_e32 v4, 26, v50
	v_add_f32_e32 v7, v31, v7
	v_ashrrev_i32_e32 v5, 31, v4
	v_lshlrev_b64 v[10:11], 9, v[4:5]
	v_addc_co_u32_e32 v3, vcc, 0, v3, vcc
	v_lshl_add_u64 v[10:11], v[52:53], 0, v[10:11]
	v_lshlrev_b64 v[4:5], 11, v[4:5]
	v_lshl_add_u64 v[4:5], v[42:43], 0, v[4:5]
	v_add_co_u32_e32 v4, vcc, s35, v4
	v_lshlrev_b32_e32 v0, 16, v0
	v_lshlrev_b32_e32 v6, 16, v6
	v_mul_f32_e32 v0, v12, v0
	v_mul_f32_e32 v6, v7, v6
	v_bfe_u32 v7, v0, 16, 1
	v_bfe_u32 v12, v6, 16, 1
	v_add3_u32 v0, v0, v7, s37
	v_add3_u32 v6, v6, v12, s37
	global_store_short_d16_hi v[2:3], v0, off offset:1792
	global_store_short_d16_hi v[2:3], v6, off offset:1856
	v_mov_b32_e32 v0, v94
	s_nop 0
	v_mov_b32_e32 v10, v95
	v_add_f32_e32 v11, v16, v8
	v_add_u32_e32 v2, 27, v50
	v_add_f32_e32 v8, v32, v8
	v_ashrrev_i32_e32 v3, 31, v2
	v_lshlrev_b64 v[6:7], 9, v[2:3]
	v_addc_co_u32_e32 v5, vcc, 0, v5, vcc
	v_lshl_add_u64 v[6:7], v[52:53], 0, v[6:7]
	v_lshlrev_b64 v[2:3], 11, v[2:3]
	v_lshl_add_u64 v[2:3], v[42:43], 0, v[2:3]
	v_add_co_u32_e32 v2, vcc, s35, v2
	v_lshlrev_b32_e32 v0, 16, v0
	v_lshlrev_b32_e32 v10, 16, v10
	v_mul_f32_e32 v0, v11, v0
	v_mul_f32_e32 v8, v8, v10
	v_bfe_u32 v10, v0, 16, 1
	v_bfe_u32 v11, v8, 16, 1
	v_add3_u32 v0, v0, v10, s37
	v_add3_u32 v8, v8, v11, s37
	global_store_short_d16_hi v[4:5], v0, off offset:1792
	global_store_short_d16_hi v[4:5], v8, off offset:1856
	v_mov_b32_e32 v0, v96
	s_nop 0
	v_mov_b32_e32 v4, v97
	v_add_f32_e32 v5, v17, v9
	v_add_f32_e32 v6, v33, v9
	v_addc_co_u32_e32 v3, vcc, 0, v3, vcc
	v_lshlrev_b32_e32 v0, 16, v0
	v_lshlrev_b32_e32 v4, 16, v4
	v_mul_f32_e32 v0, v5, v0
	v_mul_f32_e32 v4, v6, v4
	v_bfe_u32 v5, v0, 16, 1
	v_bfe_u32 v6, v4, 16, 1
	v_add3_u32 v0, v0, v5, s37
	v_add3_u32 v4, v4, v6, s37
	global_store_short_d16_hi v[2:3], v0, off offset:1792
	global_store_short_d16_hi v[2:3], v4, off offset:1856
	s_barrier
